# g3 end-of-unit g_norm ladder + sample-row rmsnorm gain-load ladders (P9 own rows, P13) de-serialised; on top of g2 rewrite + P9 epilogue wait fix
# baseline (speedup 1.0000x reference)
.LBB0_1279:
	s_or_b64 exec, exec, s[0:1]
	s_lshl_b32 s0, s4, 1
	s_add_u32 s52, s58, s0
	s_addc_u32 s53, s59, 0
	s_lshl_b32 s4, s4, 2
	v_lshl_add_u64 v[38:39], v[130:131], 0, s[4:5]
	s_waitcnt lgkmcnt(0)
	s_barrier
	global_load_dwordx4 v[98:101], v[38:39], off
	global_load_dwordx4 v[102:105], v[38:39], off offset:32
	global_load_dwordx4 v[106:109], v[38:39], off offset:64
	global_load_dwordx4 v[110:113], v[38:39], off offset:96
	ds_read2st64_b32 v[44:45], v186 offset1:1
	ds_read2st64_b32 v[46:47], v186 offset0:2 offset1:3
	ds_read2st64_b32 v[48:49], v186 offset0:4 offset1:5
	ds_read2st64_b32 v[50:51], v186 offset0:6 offset1:7
	ds_read2st64_b32 v[52:53], v187 offset1:1
	ds_read2st64_b32 v[54:55], v187 offset0:2 offset1:3
	ds_read2st64_b32 v[56:57], v187 offset0:4 offset1:5
	ds_read2st64_b32 v[58:59], v187 offset0:6 offset1:7
	s_waitcnt vmcnt(8)
	v_lshlrev_b32_e32 v40, 16, v160
	v_and_b32_e32 v41, 0xffff0000, v160
	v_mul_f32_e32 v62, 0xbfb8aa3b, v40
	v_mul_f32_e32 v63, 0xbfb8aa3b, v41
	v_exp_f32_e32 v66, v62
	v_exp_f32_e32 v67, v63
	s_waitcnt lgkmcnt(3)
	v_mov_b32_e32 v62, v52
	v_mov_b32_e32 v63, v44
	v_mov_b32_e32 v44, v53
	s_waitcnt lgkmcnt(2)
	v_mov_b32_e32 v52, v54
	v_mov_b32_e32 v53, v46
	v_mov_b32_e32 v46, v55
	s_waitcnt lgkmcnt(1)
	v_mov_b32_e32 v54, v56
	v_mov_b32_e32 v55, v48
	v_mov_b32_e32 v48, v57
	s_waitcnt lgkmcnt(0)
	v_mov_b32_e32 v56, v58
	v_mov_b32_e32 v57, v50
	v_mov_b32_e32 v50, v59
	v_pk_add_f32 v[58:59], v[62:63], 0 op_sel_hi:[1,0]
	v_lshlrev_b32_e32 v42, 16, v161
	v_pk_add_f32 v[44:45], v[58:59], v[44:45]
	v_and_b32_e32 v43, 0xffff0000, v161
	v_pk_add_f32 v[44:45], v[44:45], v[52:53]
	s_mov_b32 s0, 0x3b800000
	v_pk_add_f32 v[44:45], v[44:45], v[46:47]
	v_mul_f32_e32 v64, 0xbfb8aa3b, v42
	v_pk_add_f32 v[44:45], v[44:45], v[54:55]
	v_mul_f32_e32 v65, 0xbfb8aa3b, v43
	v_pk_add_f32 v[44:45], v[44:45], v[48:49]
	v_exp_f32_e32 v64, v64
	v_pk_add_f32 v[44:45], v[44:45], v[56:57]
	v_exp_f32_e32 v65, v65
	v_pk_add_f32 v[44:45], v[44:45], v[50:51]
	v_add_f32_e32 v66, 1.0, v66
	v_pk_fma_f32 v[44:45], v[44:45], s[0:1], v[142:143] op_sel_hi:[1,0,0]
	v_add_f32_e32 v67, 1.0, v67
	v_mul_f32_e32 v46, 0x4b800000, v45
	v_cmp_gt_f32_e64 s[0:1], s66, v45
	v_add_f32_e32 v64, 1.0, v64
	v_add_f32_e32 v65, 1.0, v65
	v_cndmask_b32_e64 v45, v45, v46, s[0:1]
	v_rsq_f32_e32 v45, v45
	v_rcp_f32_e32 v62, v66
	v_rcp_f32_e32 v63, v67
	v_rcp_f32_e32 v64, v64
	v_rcp_f32_e32 v65, v65
	v_mul_f32_e32 v48, 0x45800000, v45
	v_cndmask_b32_e64 v48, v45, v48, s[0:1]
	v_ashrrev_i32_e32 v159, 31, v158
	v_pk_mul_f32 v[18:19], v[18:19], v[48:49] op_sel_hi:[1,0]
	v_pk_mul_f32 v[20:21], v[20:21], v[48:49] op_sel_hi:[1,0]
	v_lshlrev_b64 v[60:61], 11, v[158:159]
	v_pk_mul_f32 v[40:41], v[62:63], v[40:41]
	v_pk_mul_f32 v[42:43], v[64:65], v[42:43]
	v_mov_b32_e32 v137, v125
	v_lshl_add_u64 v[60:61], s[52:53], 0, v[60:61]
	v_lshl_add_u64 v[46:47], v[60:61], 0, v[136:137]
	v_pk_mul_f32 v[22:23], v[22:23], v[48:49] op_sel_hi:[1,0]
	v_pk_mul_f32 v[24:25], v[24:25], v[48:49] op_sel_hi:[1,0]
	v_pk_mul_f32 v[26:27], v[26:27], v[48:49] op_sel_hi:[1,0]
	v_pk_mul_f32 v[28:29], v[28:29], v[48:49] op_sel_hi:[1,0]
	v_cmp_gt_f32_e64 s[0:1], s66, v44
	s_add_i32 s2, s2, s6
	s_add_i32 s64, s64, s65
	s_cmp_lt_i32 s2, s33
	v_lshl_add_u64 v[132:133], v[132:133], 0, s[42:43]
	s_waitcnt vmcnt(0)
	v_pk_mul_f32 v[18:19], v[98:99], v[18:19]
	v_pk_mul_f32 v[20:21], v[100:101], v[20:21]
	v_pk_mul_f32 v[18:19], v[40:41], v[18:19]
	v_pk_mul_f32 v[20:21], v[42:43], v[20:21]
	v_cvt_pk_bf16_f32 v18, v18, v19
	v_cvt_pk_bf16_f32 v19, v20, v21
	global_store_dwordx2 v[46:47], v[18:19], off
	v_lshlrev_b32_e32 v34, 16, v156
	v_and_b32_e32 v35, 0xffff0000, v156
	v_lshlrev_b32_e32 v36, 16, v157
	v_and_b32_e32 v37, 0xffff0000, v157
	v_mul_f32_e32 v40, 0xbfb8aa3b, v34
	v_mul_f32_e32 v41, 0xbfb8aa3b, v35
	v_mul_f32_e32 v42, 0xbfb8aa3b, v36
	v_mul_f32_e32 v43, 0xbfb8aa3b, v37
	v_exp_f32_e32 v40, v40
	v_exp_f32_e32 v41, v41
	v_exp_f32_e32 v42, v42
	v_exp_f32_e32 v43, v43
	v_add_f32_e32 v40, 1.0, v40
	v_add_f32_e32 v41, 1.0, v41
	v_add_f32_e32 v42, 1.0, v42
	v_add_f32_e32 v43, 1.0, v43
	v_rcp_f32_e32 v40, v40
	v_rcp_f32_e32 v41, v41
	v_rcp_f32_e32 v42, v42
	v_rcp_f32_e32 v43, v43
	v_pk_mul_f32 v[34:35], v[40:41], v[34:35]
	v_pk_mul_f32 v[36:37], v[42:43], v[36:37]
	v_pk_mul_f32 v[18:19], v[102:103], v[22:23]
	v_pk_mul_f32 v[20:21], v[104:105], v[24:25]
	v_pk_mul_f32 v[18:19], v[34:35], v[18:19]
	v_pk_mul_f32 v[20:21], v[36:37], v[20:21]
	v_cvt_pk_bf16_f32 v18, v18, v19
	v_cvt_pk_bf16_f32 v19, v20, v21
	global_store_dwordx2 v[46:47], v[18:19], off offset:16
	v_lshlrev_b32_e32 v22, 16, v154
	v_and_b32_e32 v23, 0xffff0000, v154
	v_lshlrev_b32_e32 v24, 16, v155
	v_and_b32_e32 v25, 0xffff0000, v155
	v_mul_f32_e32 v34, 0xbfb8aa3b, v22
	v_mul_f32_e32 v35, 0xbfb8aa3b, v23
	v_mul_f32_e32 v36, 0xbfb8aa3b, v24
	v_mul_f32_e32 v37, 0xbfb8aa3b, v25
	v_exp_f32_e32 v34, v34
	v_exp_f32_e32 v35, v35
	v_exp_f32_e32 v36, v36
	v_exp_f32_e32 v37, v37
	v_add_f32_e32 v34, 1.0, v34
	v_add_f32_e32 v35, 1.0, v35
	v_add_f32_e32 v36, 1.0, v36
	v_add_f32_e32 v37, 1.0, v37
	v_rcp_f32_e32 v34, v34
	v_rcp_f32_e32 v35, v35
	v_rcp_f32_e32 v36, v36
	v_rcp_f32_e32 v37, v37
	v_pk_mul_f32 v[22:23], v[34:35], v[22:23]
	v_pk_mul_f32 v[24:25], v[36:37], v[24:25]
	v_pk_mul_f32 v[18:19], v[106:107], v[26:27]
	v_pk_mul_f32 v[20:21], v[108:109], v[28:29]
	v_pk_mul_f32 v[18:19], v[22:23], v[18:19]
	v_pk_mul_f32 v[20:21], v[24:25], v[20:21]
	v_cvt_pk_bf16_f32 v18, v18, v19
	v_cvt_pk_bf16_f32 v19, v20, v21
	global_store_dwordx2 v[46:47], v[18:19], off offset:32
	v_lshlrev_b32_e32 v22, 16, v152
	v_and_b32_e32 v23, 0xffff0000, v152
	v_lshlrev_b32_e32 v24, 16, v153
	v_and_b32_e32 v25, 0xffff0000, v153
	v_mul_f32_e32 v26, 0xbfb8aa3b, v22
	v_mul_f32_e32 v27, 0xbfb8aa3b, v23
	v_mul_f32_e32 v28, 0xbfb8aa3b, v24
	v_mul_f32_e32 v29, 0xbfb8aa3b, v25
	v_exp_f32_e32 v26, v26
	v_exp_f32_e32 v27, v27
	v_exp_f32_e32 v28, v28
	v_exp_f32_e32 v29, v29
	v_add_f32_e32 v26, 1.0, v26
	v_add_f32_e32 v27, 1.0, v27
	v_add_f32_e32 v28, 1.0, v28
	v_add_f32_e32 v29, 1.0, v29
	v_rcp_f32_e32 v26, v26
	v_rcp_f32_e32 v27, v27
	v_rcp_f32_e32 v28, v28
	v_rcp_f32_e32 v29, v29
	v_pk_mul_f32 v[22:23], v[26:27], v[22:23]
	v_pk_mul_f32 v[26:27], v[30:31], v[48:49] op_sel_hi:[1,0]
	v_pk_mul_f32 v[24:25], v[28:29], v[24:25]
	v_pk_mul_f32 v[28:29], v[32:33], v[48:49] op_sel_hi:[1,0]
	v_mul_f32_e32 v32, 0x4b800000, v44
	v_cndmask_b32_e64 v32, v44, v32, s[0:1]
	v_rsq_f32_e32 v32, v32
	v_pk_mul_f32 v[18:19], v[110:111], v[26:27]
	v_pk_mul_f32 v[20:21], v[112:113], v[28:29]
	v_pk_mul_f32 v[18:19], v[22:23], v[18:19]
	v_pk_mul_f32 v[20:21], v[24:25], v[20:21]
	v_cvt_pk_bf16_f32 v18, v18, v19
	v_cvt_pk_bf16_f32 v19, v20, v21
	global_store_dwordx2 v[46:47], v[18:19], off offset:48
	v_lshlrev_b32_e32 v24, 16, v150
	v_and_b32_e32 v25, 0xffff0000, v150
	v_mul_f32_e32 v28, 0xbfb8aa3b, v24
	v_mul_f32_e32 v29, 0xbfb8aa3b, v25
	v_exp_f32_e32 v28, v28
	v_exp_f32_e32 v29, v29
	v_lshlrev_b32_e32 v26, 16, v151
	v_and_b32_e32 v27, 0xffff0000, v151
	v_mul_f32_e32 v30, 0xbfb8aa3b, v26
	v_mul_f32_e32 v31, 0xbfb8aa3b, v27
	v_exp_f32_e32 v30, v30
	v_exp_f32_e32 v31, v31
	v_add_f32_e32 v28, 1.0, v28
	v_add_f32_e32 v29, 1.0, v29
	v_rcp_f32_e32 v28, v28
	v_rcp_f32_e32 v29, v29
	v_add_f32_e32 v30, 1.0, v30
	v_add_f32_e32 v31, 1.0, v31
	v_rcp_f32_e32 v30, v30
	v_rcp_f32_e32 v31, v31
	v_pk_mul_f32 v[24:25], v[28:29], v[24:25]
	v_mul_f32_e32 v28, 0x45800000, v32
	v_or_b32_e32 v22, s67, v185
	v_cndmask_b32_e64 v28, v32, v28, s[0:1]
	v_ashrrev_i32_e32 v23, 31, v22
	v_pk_mul_f32 v[2:3], v[2:3], v[28:29] op_sel_hi:[1,0]
	v_pk_mul_f32 v[4:5], v[4:5], v[28:29] op_sel_hi:[1,0]
	v_lshlrev_b64 v[22:23], 11, v[22:23]
	v_pk_mul_f32 v[26:27], v[30:31], v[26:27]
	v_lshl_add_u64 v[22:23], s[52:53], 0, v[22:23]
	v_lshl_add_u64 v[22:23], v[22:23], 0, v[136:137]
	v_pk_mul_f32 v[6:7], v[6:7], v[28:29] op_sel_hi:[1,0]
	v_pk_mul_f32 v[8:9], v[8:9], v[28:29] op_sel_hi:[1,0]
	v_pk_mul_f32 v[10:11], v[10:11], v[28:29] op_sel_hi:[1,0]
	v_pk_mul_f32 v[12:13], v[12:13], v[28:29] op_sel_hi:[1,0]
	v_pk_mul_f32 v[2:3], v[98:99], v[2:3]
	v_pk_mul_f32 v[4:5], v[100:101], v[4:5]
	v_pk_mul_f32 v[2:3], v[24:25], v[2:3]
	v_pk_mul_f32 v[4:5], v[26:27], v[4:5]
	v_cvt_pk_bf16_f32 v2, v2, v3
	v_cvt_pk_bf16_f32 v3, v4, v5
	global_store_dwordx2 v[22:23], v[2:3], off
	v_lshlrev_b32_e32 v18, 16, v148
	v_and_b32_e32 v19, 0xffff0000, v148
	v_lshlrev_b32_e32 v20, 16, v149
	v_and_b32_e32 v21, 0xffff0000, v149
	v_mul_f32_e32 v24, 0xbfb8aa3b, v18
	v_mul_f32_e32 v25, 0xbfb8aa3b, v19
	v_mul_f32_e32 v26, 0xbfb8aa3b, v20
	v_mul_f32_e32 v27, 0xbfb8aa3b, v21
	v_exp_f32_e32 v24, v24
	v_exp_f32_e32 v25, v25
	v_exp_f32_e32 v26, v26
	v_exp_f32_e32 v27, v27
	v_add_f32_e32 v24, 1.0, v24
	v_add_f32_e32 v25, 1.0, v25
	v_add_f32_e32 v26, 1.0, v26
	v_add_f32_e32 v27, 1.0, v27
	v_rcp_f32_e32 v24, v24
	v_rcp_f32_e32 v25, v25
	v_rcp_f32_e32 v26, v26
	v_rcp_f32_e32 v27, v27
	v_pk_mul_f32 v[18:19], v[24:25], v[18:19]
	v_pk_mul_f32 v[20:21], v[26:27], v[20:21]
	v_pk_mul_f32 v[2:3], v[102:103], v[6:7]
	v_pk_mul_f32 v[4:5], v[104:105], v[8:9]
	v_pk_mul_f32 v[2:3], v[18:19], v[2:3]
	v_pk_mul_f32 v[4:5], v[20:21], v[4:5]
	v_cvt_pk_bf16_f32 v2, v2, v3
	v_cvt_pk_bf16_f32 v3, v4, v5
	global_store_dwordx2 v[22:23], v[2:3], off offset:16
	v_lshlrev_b32_e32 v6, 16, v146
	v_and_b32_e32 v7, 0xffff0000, v146
	v_lshlrev_b32_e32 v8, 16, v147
	v_and_b32_e32 v9, 0xffff0000, v147
	v_mul_f32_e32 v18, 0xbfb8aa3b, v6
	v_mul_f32_e32 v19, 0xbfb8aa3b, v7
	v_mul_f32_e32 v20, 0xbfb8aa3b, v8
	v_mul_f32_e32 v21, 0xbfb8aa3b, v9
	v_exp_f32_e32 v18, v18
	v_exp_f32_e32 v19, v19
	v_exp_f32_e32 v20, v20
	v_exp_f32_e32 v21, v21
	v_add_f32_e32 v18, 1.0, v18
	v_add_f32_e32 v19, 1.0, v19
	v_add_f32_e32 v20, 1.0, v20
	v_add_f32_e32 v21, 1.0, v21
	v_rcp_f32_e32 v18, v18
	v_rcp_f32_e32 v19, v19
	v_rcp_f32_e32 v20, v20
	v_rcp_f32_e32 v21, v21
	v_pk_mul_f32 v[6:7], v[18:19], v[6:7]
	v_pk_mul_f32 v[8:9], v[20:21], v[8:9]
	v_pk_mul_f32 v[2:3], v[106:107], v[10:11]
	v_pk_mul_f32 v[4:5], v[108:109], v[12:13]
	v_pk_mul_f32 v[2:3], v[6:7], v[2:3]
	v_pk_mul_f32 v[4:5], v[8:9], v[4:5]
	v_cvt_pk_bf16_f32 v2, v2, v3
	v_cvt_pk_bf16_f32 v3, v4, v5
	global_store_dwordx2 v[22:23], v[2:3], off offset:32
	v_lshlrev_b32_e32 v6, 16, v144
	v_and_b32_e32 v7, 0xffff0000, v144
	v_lshlrev_b32_e32 v8, 16, v145
	v_and_b32_e32 v9, 0xffff0000, v145
	v_mul_f32_e32 v10, 0xbfb8aa3b, v6
	v_mul_f32_e32 v11, 0xbfb8aa3b, v7
	v_mul_f32_e32 v12, 0xbfb8aa3b, v8
	v_mul_f32_e32 v13, 0xbfb8aa3b, v9
	v_exp_f32_e32 v10, v10
	v_exp_f32_e32 v11, v11
	v_exp_f32_e32 v12, v12
	v_exp_f32_e32 v13, v13
	v_add_f32_e32 v10, 1.0, v10
	v_add_f32_e32 v11, 1.0, v11
	v_add_f32_e32 v12, 1.0, v12
	v_add_f32_e32 v13, 1.0, v13
	v_rcp_f32_e32 v10, v10
	v_rcp_f32_e32 v11, v11
	v_rcp_f32_e32 v12, v12
	v_rcp_f32_e32 v13, v13
	v_pk_mul_f32 v[6:7], v[10:11], v[6:7]
	v_pk_mul_f32 v[10:11], v[14:15], v[28:29] op_sel_hi:[1,0]
	v_pk_mul_f32 v[8:9], v[12:13], v[8:9]
	v_pk_mul_f32 v[12:13], v[16:17], v[28:29] op_sel_hi:[1,0]
	v_pk_mul_f32 v[2:3], v[110:111], v[10:11]
	v_pk_mul_f32 v[4:5], v[112:113], v[12:13]
	v_pk_mul_f32 v[2:3], v[6:7], v[2:3]
	v_pk_mul_f32 v[4:5], v[8:9], v[4:5]
	v_cvt_pk_bf16_f32 v2, v2, v3
	v_cvt_pk_bf16_f32 v3, v4, v5
	global_store_dwordx2 v[22:23], v[2:3], off offset:48
	s_nop 0
	s_barrier
	s_cbranch_scc0 .LBB0_1284

.LBB0_2270:
	v_lshl_add_u64 v[10:11], s[80:81], 0, v[6:7]
	v_add_co_u32_e32 v28, vcc, 0x4790a000, v10
	v_add_co_u32_e64 v32, s[0:1], s15, v10
	s_nop 0
	v_addc_co_u32_e32 v29, vcc, 0, v11, vcc
	v_addc_co_u32_e64 v33, s[0:1], 0, v11, s[0:1]
	global_load_dwordx4 v[20:23], v[28:29], off offset:1024
	global_load_dwordx4 v[24:27], v[28:29], off offset:2048
	s_nop 0
	global_load_dwordx4 v[28:31], v[28:29], off offset:3072
	s_nop 0
	global_load_dwordx4 v[32:35], v[32:33], off
	s_add_i32 s12, s12, 8
	global_load_dwordx4 v[36:39], v[2:3], off
	s_cmpk_lt_u32 s12, 0x4000
	s_cselect_b32 s1, s11, s14
	s_cselect_b32 s0, s10, s13
	global_load_dwordx4 v[40:43], v17, s[0:1]
	global_load_dwordx4 v[44:47], v17, s[0:1] offset:1024
	global_load_dwordx4 v[48:51], v17, s[0:1] offset:2048
	global_load_dwordx4 v[52:55], v17, s[0:1] offset:3072
	global_load_dwordx4 v[76:79], v[2:3], off offset:1024
	global_load_dwordx4 v[80:83], v[2:3], off offset:2048
	global_load_dwordx4 v[84:87], v[2:3], off offset:3072
	global_load_dwordx4 v[88:91], v[4:5], off
	global_load_dwordx4 v[92:95], v[4:5], off offset:1024
	global_load_dwordx4 v[96:99], v[4:5], off offset:2048
	global_load_dwordx4 v[100:103], v[4:5], off offset:3072
	v_add_co_u32_e32 v56, vcc, s17, v10
	s_add_u32 s10, s10, 0x8000
	s_nop 0
	v_addc_co_u32_e32 v57, vcc, 0, v11, vcc
	s_addc_u32 s11, s11, 0
	s_add_u32 s13, s13, 0x8000
	s_addc_u32 s14, s14, 0
	v_lshl_add_u64 v[6:7], v[6:7], 0, s[6:7]
	s_cmpk_lt_u32 s12, 0x4018
	s_waitcnt vmcnt(15)
	v_pk_mul_f32 v[58:59], v[22:23], v[22:23]
	v_pk_mul_f32 v[60:61], v[20:21], v[20:21]
	s_waitcnt vmcnt(14)
	v_pk_mul_f32 v[62:63], v[26:27], v[26:27]
	v_pk_mul_f32 v[64:65], v[24:25], v[24:25]
	v_pk_mov_b32 v[70:71], v[60:61], v[58:59] op_sel:[1,0]
	v_mov_b32_e32 v61, v59
	v_pk_mov_b32 v[58:59], v[64:65], v[62:63] op_sel:[1,0]
	v_mov_b32_e32 v65, v63
	s_waitcnt vmcnt(12)
	v_mul_f32_e32 v69, v33, v33
	v_mul_f32_e32 v66, v29, v29
	v_mul_f32_e32 v68, v31, v31
	v_pk_add_f32 v[60:61], v[70:71], v[60:61]
	v_pk_add_f32 v[58:59], v[58:59], v[64:65]
	v_mul_f32_e32 v19, v32, v32
	v_mul_f32_e32 v72, v34, v34
	v_mul_f32_e32 v73, v35, v35
	v_pk_fma_f32 v[62:63], v[28:29], v[28:29], v[66:67] op_sel_hi:[1,1,0]
	v_pk_fma_f32 v[66:67], v[30:31], v[30:31], v[68:69] op_sel_hi:[1,1,0]
	v_pk_add_f32 v[60:61], v[60:61], v[60:61] op_sel:[0,1] op_sel_hi:[1,0]
	v_pk_add_f32 v[58:59], v[58:59], v[58:59] op_sel:[0,1] op_sel_hi:[1,0]
	v_mov_b32_e32 v63, v72
	v_mov_b32_e32 v67, v73
	v_mov_b32_e32 v61, v19
	v_mov_b32_e32 v59, v69
	v_pk_add_f32 v[62:63], v[62:63], v[66:67]
	v_pk_add_f32 v[58:59], v[60:61], v[58:59]
	s_nop 0
	v_pk_add_f32 v[58:59], v[58:59], v[62:63]
	s_nop 0
	v_add_f32_e32 v19, v58, v59
	ds_bpermute_b32 v58, v1, v19
	s_waitcnt lgkmcnt(0)
	v_add_f32_e32 v19, v19, v58
	ds_bpermute_b32 v58, v12, v19
	s_waitcnt lgkmcnt(0)
	v_add_f32_e32 v19, v19, v58
	ds_bpermute_b32 v58, v13, v19
	s_waitcnt lgkmcnt(0)
	v_add_f32_e32 v19, v19, v58
	ds_bpermute_b32 v58, v14, v19
	s_waitcnt lgkmcnt(0)
	v_add_f32_e32 v19, v19, v58
	ds_bpermute_b32 v58, v15, v19
	s_waitcnt lgkmcnt(0)
	v_add_f32_e32 v19, v19, v58
	ds_bpermute_b32 v58, v16, v19
	s_waitcnt lgkmcnt(0)
	v_add_f32_e32 v19, v19, v58
	v_fmamk_f32 v19, v19, 0x3a800000, v18
	v_mul_f32_e32 v58, 0x4b800000, v19
	v_cmp_gt_f32_e32 vcc, s16, v19
	s_nop 1
	v_cndmask_b32_e32 v19, v19, v58, vcc
	v_rsq_f32_e32 v19, v19
	s_nop 0
	v_mul_f32_e32 v58, 0x45800000, v19
	v_cndmask_b32_e32 v58, v19, v58, vcc
	v_pk_mul_f32 v[20:21], v[20:21], v[58:59] op_sel_hi:[1,0]
	v_pk_mul_f32 v[22:23], v[22:23], v[58:59] op_sel_hi:[1,0]
	s_waitcnt vmcnt(10)
	v_pk_fma_f32 v[20:21], v[36:37], v[20:21], v[40:41]
	v_pk_fma_f32 v[22:23], v[38:39], v[22:23], v[42:43]
	global_store_dwordx4 v[56:57], v[20:23], off offset:1024
	v_pk_mul_f32 v[26:27], v[26:27], v[58:59] op_sel_hi:[1,0]
	v_pk_mul_f32 v[24:25], v[24:25], v[58:59] op_sel_hi:[1,0]
	v_pk_mul_f32 v[30:31], v[30:31], v[58:59] op_sel_hi:[1,0]
	v_pk_mul_f32 v[28:29], v[28:29], v[58:59] op_sel_hi:[1,0]
	v_add_co_u32_e32 v10, vcc, s18, v10
	v_pk_mul_f32 v[32:33], v[32:33], v[58:59] op_sel_hi:[1,0]
	v_pk_mul_f32 v[34:35], v[34:35], v[58:59] op_sel_hi:[1,0]
	v_addc_co_u32_e32 v11, vcc, 0, v11, vcc
	v_pk_mul_f32 v[42:43], v[22:23], v[22:23]
	v_lshl_add_u64 v[40:41], s[80:81], 0, v[8:9]
	v_add_co_u32_e32 v40, vcc, s19, v40
	v_lshl_add_u64 v[8:9], v[8:9], 0, s[8:9]
	s_nop 0
	v_addc_co_u32_e32 v41, vcc, 0, v41, vcc
	s_waitcnt vmcnt(1)
	v_pk_fma_f32 v[24:25], v[76:77], v[24:25], v[44:45]
	v_pk_fma_f32 v[26:27], v[78:79], v[26:27], v[46:47]
	global_store_dwordx4 v[56:57], v[24:27], off offset:2048
	v_pk_fma_f32 v[28:29], v[80:81], v[28:29], v[48:49]
	v_pk_fma_f32 v[30:31], v[82:83], v[30:31], v[50:51]
	global_store_dwordx4 v[56:57], v[28:31], off offset:3072
	v_pk_fma_f32 v[34:35], v[86:87], v[34:35], v[54:55]
	v_pk_fma_f32 v[32:33], v[84:85], v[32:33], v[52:53]
	global_store_dwordx4 v[10:11], v[32:35], off
	v_pk_mul_f32 v[10:11], v[20:21], v[20:21]
	s_nop 0
	v_pk_mov_b32 v[44:45], v[10:11], v[42:43] op_sel:[1,0]
	v_mov_b32_e32 v11, v43
	v_pk_add_f32 v[10:11], v[44:45], v[10:11]
	v_pk_mul_f32 v[42:43], v[24:25], v[24:25]
	v_pk_mul_f32 v[44:45], v[26:27], v[26:27]
	v_pk_add_f32 v[10:11], v[10:11], v[10:11] op_sel_hi:[0,1]
	v_pk_mov_b32 v[46:47], v[42:43], v[44:45] op_sel:[1,0]
	v_mov_b32_e32 v43, v45
	v_pk_add_f32 v[42:43], v[46:47], v[42:43]
	v_mul_f32_e32 v10, v28, v28
	v_pk_add_f32 v[42:43], v[42:43], v[42:43] op_sel_hi:[0,1]
	v_mul_f32_e32 v42, v30, v30
	v_pk_fma_f32 v[44:45], v[28:29], v[28:29], v[10:11] op_sel_hi:[1,1,0]
	v_pk_fma_f32 v[46:47], v[30:31], v[30:31], v[42:43] op_sel_hi:[1,1,0]
	v_mul_f32_e32 v44, v32, v32
	v_mul_f32_e32 v46, v33, v33
	v_mul_f32_e32 v10, v34, v34
	v_mul_f32_e32 v42, v35, v35
	v_pk_add_f32 v[44:45], v[44:45], v[46:47]
	v_pk_add_f32 v[10:11], v[10:11], v[42:43]
	s_nop 0
	v_pk_add_f32 v[10:11], v[44:45], v[10:11]
	s_nop 0
	v_add_f32_e32 v10, v10, v11
	ds_bpermute_b32 v11, v1, v10
	s_waitcnt lgkmcnt(0)
	v_add_f32_e32 v10, v10, v11
	ds_bpermute_b32 v11, v12, v10
	s_waitcnt lgkmcnt(0)
	v_add_f32_e32 v10, v10, v11
	ds_bpermute_b32 v11, v13, v10
	s_waitcnt lgkmcnt(0)
	v_add_f32_e32 v10, v10, v11
	ds_bpermute_b32 v11, v14, v10
	s_waitcnt lgkmcnt(0)
	v_add_f32_e32 v10, v10, v11
	ds_bpermute_b32 v11, v15, v10
	s_waitcnt lgkmcnt(0)
	v_add_f32_e32 v10, v10, v11
	ds_bpermute_b32 v11, v16, v10
	s_waitcnt lgkmcnt(0)
	v_add_f32_e32 v10, v10, v11
	v_fmamk_f32 v10, v10, 0x3a800000, v18
	v_mul_f32_e32 v11, 0x4b800000, v10
	v_cmp_gt_f32_e32 vcc, s16, v10
	s_nop 1
	v_cndmask_b32_e32 v10, v10, v11, vcc
	v_rsq_f32_e32 v10, v10
	s_nop 0
	v_mul_f32_e32 v11, 0x45800000, v10
	v_cndmask_b32_e32 v10, v10, v11, vcc
	v_pk_mul_f32 v[20:21], v[20:21], v[10:11] op_sel_hi:[1,0]
	v_pk_mul_f32 v[22:23], v[22:23], v[10:11] op_sel_hi:[1,0]
	v_pk_mul_f32 v[24:25], v[24:25], v[10:11] op_sel_hi:[1,0]
	v_pk_mul_f32 v[26:27], v[26:27], v[10:11] op_sel_hi:[1,0]
	v_pk_mul_f32 v[20:21], v[88:89], v[20:21]
	v_pk_mul_f32 v[22:23], v[90:91], v[22:23]
	v_cvt_pk_bf16_f32 v20, v20, v21
	v_cvt_pk_bf16_f32 v21, v22, v23
	global_store_dwordx2 v[40:41], v[20:21], off offset:1024
	v_pk_mul_f32 v[20:21], v[92:93], v[24:25]
	v_pk_mul_f32 v[22:23], v[94:95], v[26:27]
	v_cvt_pk_bf16_f32 v20, v20, v21
	v_cvt_pk_bf16_f32 v21, v22, v23
	global_store_dwordx2 v[40:41], v[20:21], off offset:1536
	v_pk_mul_f32 v[24:25], v[28:29], v[10:11] op_sel_hi:[1,0]
	v_pk_mul_f32 v[26:27], v[30:31], v[10:11] op_sel_hi:[1,0]
	v_pk_mul_f32 v[20:21], v[96:97], v[24:25]
	v_pk_mul_f32 v[22:23], v[98:99], v[26:27]
	v_cvt_pk_bf16_f32 v20, v20, v21
	v_cvt_pk_bf16_f32 v21, v22, v23
	global_store_dwordx2 v[40:41], v[20:21], off offset:2048
	v_pk_mul_f32 v[24:25], v[32:33], v[10:11] op_sel_hi:[1,0]
	v_pk_mul_f32 v[10:11], v[34:35], v[10:11] op_sel_hi:[1,0]
	v_pk_mul_f32 v[20:21], v[100:101], v[24:25]
	v_pk_mul_f32 v[10:11], v[102:103], v[10:11]
	v_cvt_pk_bf16_f32 v20, v20, v21
	v_cvt_pk_bf16_f32 v21, v10, v11
	global_store_dwordx2 v[40:41], v[20:21], off offset:2560
	s_cbranch_scc1 .LBB0_2270

.LBB0_2889:
	v_lshl_add_u64 v[8:9], s[80:81], 0, v[4:5]
	v_add_co_u32_e32 v34, vcc, 0x4790a000, v8
	v_add_co_u32_e64 v36, s[0:1], s17, v8
	s_nop 0
	v_addc_co_u32_e32 v35, vcc, 0, v9, vcc
	v_addc_co_u32_e64 v37, s[0:1], 0, v9, s[0:1]
	global_load_dwordx4 v[18:21], v[34:35], off offset:1024
	global_load_dwordx4 v[22:25], v[34:35], off offset:2048
	global_load_dwordx4 v[26:29], v[34:35], off offset:3072
	global_load_dwordx4 v[30:33], v[36:37], off
	s_add_i32 s16, s16, 8
	global_load_dwordx4 v[34:37], v[0:1], off
	s_add_u32 s0, s80, s14
	s_addc_u32 s1, s81, s15
	global_load_dwordx4 v[38:41], v16, s[0:1]
	global_load_dwordx4 v[42:45], v16, s[0:1] offset:1024
	global_load_dwordx4 v[46:49], v16, s[0:1] offset:2048
	global_load_dwordx4 v[50:53], v16, s[0:1] offset:3072
	global_load_dwordx4 v[76:79], v[0:1], off offset:1024
	global_load_dwordx4 v[80:83], v[0:1], off offset:2048
	global_load_dwordx4 v[84:87], v[0:1], off offset:3072
	global_load_dwordx4 v[88:91], v[2:3], off
	global_load_dwordx4 v[92:95], v[2:3], off offset:1024
	global_load_dwordx4 v[96:99], v[2:3], off offset:2048
	global_load_dwordx4 v[100:103], v[2:3], off offset:3072
	v_add_co_u32_e32 v54, vcc, s19, v8
	s_add_u32 s14, s14, 0x8000
	s_nop 0
	v_addc_co_u32_e32 v55, vcc, 0, v9, vcc
	s_addc_u32 s15, s15, 0
	v_lshl_add_u64 v[4:5], v[4:5], 0, s[10:11]
	s_cmpk_lt_u32 s16, 0x4018
	s_waitcnt vmcnt(15)
	v_pk_mul_f32 v[56:57], v[20:21], v[20:21]
	v_pk_mul_f32 v[58:59], v[18:19], v[18:19]
	s_waitcnt vmcnt(14)
	v_pk_mul_f32 v[60:61], v[24:25], v[24:25]
	v_pk_mul_f32 v[62:63], v[22:23], v[22:23]
	v_pk_mov_b32 v[68:69], v[58:59], v[56:57] op_sel:[1,0]
	v_mov_b32_e32 v59, v57
	v_pk_mov_b32 v[56:57], v[62:63], v[60:61] op_sel:[1,0]
	v_mov_b32_e32 v63, v61
	s_waitcnt vmcnt(12)
	v_mul_f32_e32 v67, v30, v30
	v_mul_f32_e32 v64, v27, v27
	v_mul_f32_e32 v66, v29, v29
	v_pk_add_f32 v[58:59], v[68:69], v[58:59]
	v_pk_add_f32 v[56:57], v[56:57], v[62:63]
	v_mul_f32_e32 v70, v31, v31
	v_mul_f32_e32 v71, v32, v32
	v_mul_f32_e32 v72, v33, v33
	v_pk_fma_f32 v[60:61], v[26:27], v[26:27], v[64:65] op_sel_hi:[1,1,0]
	v_pk_fma_f32 v[64:65], v[28:29], v[28:29], v[66:67] op_sel_hi:[1,1,0]
	v_pk_add_f32 v[58:59], v[58:59], v[58:59] op_sel:[0,1] op_sel_hi:[1,0]
	v_pk_add_f32 v[56:57], v[56:57], v[56:57] op_sel:[0,1] op_sel_hi:[1,0]
	v_mov_b32_e32 v61, v71
	v_mov_b32_e32 v65, v72
	v_mov_b32_e32 v59, v67
	v_mov_b32_e32 v57, v70
	v_pk_add_f32 v[60:61], v[60:61], v[64:65]
	v_pk_add_f32 v[56:57], v[58:59], v[56:57]
	s_nop 0
	v_pk_add_f32 v[56:57], v[56:57], v[60:61]
	s_nop 0
	v_add_f32_e32 v56, v56, v57
	ds_bpermute_b32 v57, v10, v56
	s_waitcnt lgkmcnt(0)
	v_add_f32_e32 v56, v56, v57
	ds_bpermute_b32 v57, v11, v56
	s_waitcnt lgkmcnt(0)
	v_add_f32_e32 v56, v56, v57
	ds_bpermute_b32 v57, v12, v56
	s_waitcnt lgkmcnt(0)
	v_add_f32_e32 v56, v56, v57
	ds_bpermute_b32 v57, v13, v56
	s_waitcnt lgkmcnt(0)
	v_add_f32_e32 v56, v56, v57
	ds_bpermute_b32 v57, v14, v56
	s_waitcnt lgkmcnt(0)
	v_add_f32_e32 v56, v56, v57
	ds_bpermute_b32 v57, v15, v56
	s_waitcnt lgkmcnt(0)
	v_add_f32_e32 v56, v56, v57
	v_fmamk_f32 v56, v56, 0x3a800000, v17
	v_mul_f32_e32 v57, 0x4b800000, v56
	v_cmp_gt_f32_e32 vcc, s18, v56
	s_nop 1
	v_cndmask_b32_e32 v56, v56, v57, vcc
	v_rsq_f32_e32 v56, v56
	s_nop 0
	v_mul_f32_e32 v57, 0x45800000, v56
	v_cndmask_b32_e32 v56, v56, v57, vcc
	v_pk_mul_f32 v[18:19], v[18:19], v[56:57] op_sel_hi:[1,0]
	v_pk_mul_f32 v[20:21], v[20:21], v[56:57] op_sel_hi:[1,0]
	s_waitcnt vmcnt(10)
	v_pk_fma_f32 v[18:19], v[34:35], v[18:19], v[38:39]
	v_pk_fma_f32 v[20:21], v[36:37], v[20:21], v[40:41]
	global_store_dwordx4 v[54:55], v[18:21], off offset:1024
	v_pk_mul_f32 v[24:25], v[24:25], v[56:57] op_sel_hi:[1,0]
	v_pk_mul_f32 v[22:23], v[22:23], v[56:57] op_sel_hi:[1,0]
	v_pk_mul_f32 v[28:29], v[28:29], v[56:57] op_sel_hi:[1,0]
	v_pk_mul_f32 v[26:27], v[26:27], v[56:57] op_sel_hi:[1,0]
	v_add_co_u32_e32 v8, vcc, s20, v8
	v_pk_mul_f32 v[30:31], v[30:31], v[56:57] op_sel_hi:[1,0]
	v_pk_mul_f32 v[32:33], v[32:33], v[56:57] op_sel_hi:[1,0]
	v_addc_co_u32_e32 v9, vcc, 0, v9, vcc
	v_pk_mul_f32 v[40:41], v[20:21], v[20:21]
	v_lshl_add_u64 v[38:39], s[80:81], 0, v[6:7]
	v_add_co_u32_e32 v38, vcc, s21, v38
	v_lshl_add_u64 v[6:7], v[6:7], 0, s[12:13]
	s_nop 0
	v_addc_co_u32_e32 v39, vcc, 0, v39, vcc
	s_waitcnt vmcnt(1)
	v_pk_fma_f32 v[22:23], v[76:77], v[22:23], v[42:43]
	v_pk_fma_f32 v[24:25], v[78:79], v[24:25], v[44:45]
	global_store_dwordx4 v[54:55], v[22:25], off offset:2048
	v_pk_fma_f32 v[26:27], v[80:81], v[26:27], v[46:47]
	v_pk_fma_f32 v[28:29], v[82:83], v[28:29], v[48:49]
	global_store_dwordx4 v[54:55], v[26:29], off offset:3072
	v_pk_fma_f32 v[32:33], v[86:87], v[32:33], v[52:53]
	v_pk_fma_f32 v[30:31], v[84:85], v[30:31], v[50:51]
	global_store_dwordx4 v[8:9], v[30:33], off
	v_pk_mul_f32 v[8:9], v[18:19], v[18:19]
	s_nop 0
	v_pk_mov_b32 v[42:43], v[8:9], v[40:41] op_sel:[1,0]
	v_mov_b32_e32 v9, v41
	v_pk_add_f32 v[8:9], v[42:43], v[8:9]
	v_pk_mul_f32 v[40:41], v[22:23], v[22:23]
	v_pk_mul_f32 v[42:43], v[24:25], v[24:25]
	v_pk_add_f32 v[8:9], v[8:9], v[8:9] op_sel_hi:[0,1]
	v_pk_mov_b32 v[44:45], v[40:41], v[42:43] op_sel:[1,0]
	v_mov_b32_e32 v41, v43
	v_pk_add_f32 v[40:41], v[44:45], v[40:41]
	v_mul_f32_e32 v8, v26, v26
	v_pk_add_f32 v[40:41], v[40:41], v[40:41] op_sel_hi:[0,1]
	v_mul_f32_e32 v40, v28, v28
	v_pk_fma_f32 v[42:43], v[26:27], v[26:27], v[8:9] op_sel_hi:[1,1,0]
	v_pk_fma_f32 v[44:45], v[28:29], v[28:29], v[40:41] op_sel_hi:[1,1,0]
	v_mul_f32_e32 v42, v30, v30
	v_mul_f32_e32 v44, v31, v31
	v_mul_f32_e32 v8, v32, v32
	v_mul_f32_e32 v40, v33, v33
	v_pk_add_f32 v[42:43], v[42:43], v[44:45]
	v_pk_add_f32 v[8:9], v[8:9], v[40:41]
	s_nop 0
	v_pk_add_f32 v[8:9], v[42:43], v[8:9]
	s_nop 0
	v_add_f32_e32 v8, v8, v9
	ds_bpermute_b32 v9, v10, v8
	s_waitcnt lgkmcnt(0)
	v_add_f32_e32 v8, v8, v9
	ds_bpermute_b32 v9, v11, v8
	s_waitcnt lgkmcnt(0)
	v_add_f32_e32 v8, v8, v9
	ds_bpermute_b32 v9, v12, v8
	s_waitcnt lgkmcnt(0)
	v_add_f32_e32 v8, v8, v9
	ds_bpermute_b32 v9, v13, v8
	s_waitcnt lgkmcnt(0)
	v_add_f32_e32 v8, v8, v9
	ds_bpermute_b32 v9, v14, v8
	s_waitcnt lgkmcnt(0)
	v_add_f32_e32 v8, v8, v9
	ds_bpermute_b32 v9, v15, v8
	s_waitcnt lgkmcnt(0)
	v_add_f32_e32 v8, v8, v9
	v_fmamk_f32 v8, v8, 0x3a800000, v17
	v_mul_f32_e32 v9, 0x4b800000, v8
	v_cmp_gt_f32_e32 vcc, s18, v8
	s_nop 1
	v_cndmask_b32_e32 v8, v8, v9, vcc
	v_rsq_f32_e32 v8, v8
	s_nop 0
	v_mul_f32_e32 v9, 0x45800000, v8
	v_cndmask_b32_e32 v8, v8, v9, vcc
	v_pk_mul_f32 v[18:19], v[18:19], v[8:9] op_sel_hi:[1,0]
	v_pk_mul_f32 v[20:21], v[20:21], v[8:9] op_sel_hi:[1,0]
	v_pk_mul_f32 v[22:23], v[22:23], v[8:9] op_sel_hi:[1,0]
	v_pk_mul_f32 v[24:25], v[24:25], v[8:9] op_sel_hi:[1,0]
	v_pk_mul_f32 v[18:19], v[88:89], v[18:19]
	v_pk_mul_f32 v[20:21], v[90:91], v[20:21]
	v_cvt_pk_bf16_f32 v18, v18, v19
	v_cvt_pk_bf16_f32 v19, v20, v21
	global_store_dwordx2 v[38:39], v[18:19], off offset:1024
	v_pk_mul_f32 v[18:19], v[92:93], v[22:23]
	v_pk_mul_f32 v[20:21], v[94:95], v[24:25]
	v_cvt_pk_bf16_f32 v18, v18, v19
	v_cvt_pk_bf16_f32 v19, v20, v21
	global_store_dwordx2 v[38:39], v[18:19], off offset:1536
	v_pk_mul_f32 v[22:23], v[26:27], v[8:9] op_sel_hi:[1,0]
	v_pk_mul_f32 v[24:25], v[28:29], v[8:9] op_sel_hi:[1,0]
	v_pk_mul_f32 v[18:19], v[96:97], v[22:23]
	v_pk_mul_f32 v[20:21], v[98:99], v[24:25]
	v_cvt_pk_bf16_f32 v18, v18, v19
	v_cvt_pk_bf16_f32 v19, v20, v21
	global_store_dwordx2 v[38:39], v[18:19], off offset:2048
	v_pk_mul_f32 v[22:23], v[30:31], v[8:9] op_sel_hi:[1,0]
	v_pk_mul_f32 v[8:9], v[32:33], v[8:9] op_sel_hi:[1,0]
	v_pk_mul_f32 v[18:19], v[100:101], v[22:23]
	v_pk_mul_f32 v[8:9], v[102:103], v[8:9]
	v_cvt_pk_bf16_f32 v18, v18, v19
	v_cvt_pk_bf16_f32 v19, v8, v9
	global_store_dwordx2 v[38:39], v[18:19], off offset:2560
	s_cbranch_scc1 .LBB0_2889
